# final-norm split-K partial fold: 44 serialized load+wait pairs replaced by two batches with counted vmcnt (same add order); S5a LDS reads pipelined; saddr LDS-DMA in GEMM K-loops
# speedup vs baseline: 1.0063x; 1.0036x over previous
; __device__ __forceinline__ float bflo(unsigned w) { return __uint_as_float(w << 16); }
; __device__ __forceinline__ float bfhi(unsigned w) { return __uint_as_float(w & 0xffff0000u); }
; __device__ void final_norm(const Params& p, const bf16_t* hb, const float* gain, float* out) {
;     ...
;     for (int orow = p.bid * 8 + wave; orow < NBATCH * SEQ; orow += p.nblk * 8) {
;         const int b = orow >> 12, tt = orow & 4095, row = b * TB + NMETA + tt; const bf16_t* hp = hb + (size_t)row * DM; f32x4 v[4]; float ss = 0.f;
; #pragma unroll
;         for (int i = 0; i < 4; ++i) { const u32x2 w = *(const u32x2*)(hp + lane * 4 + 256 * i); v[i] = (f32x4){bflo(w.x), bfhi(w.x), bflo(w.y), bfhi(w.y)}; }
;         if (row >= MP - 256) { const float* pt = (const float*)(p.ws + WS_PART) + (size_t)(row - (MP - 256)) * DM + lane * 4;
;             for (int sl = 0; sl < 11; ++sl)
; #pragma unroll
;                 for (int i = 0; i < 4; ++i) v[i] += *(const f32x4*)(pt + (size_t)sl * 256 * DM + 256 * i); }
.LBB0_17:
	v_ashrrev_i32_e32 v0, 12, v44
	v_and_b32_e32 v18, 0xfff, v44
	v_mul_i32_i24_e32 v0, 0x1020, v0
	v_add3_u32 v18, v18, v0, 16
	v_ashrrev_i32_e32 v19, 31, v18
	v_lshlrev_b64 v[20:21], 11, v[18:19]
	v_lshl_add_u64 v[20:21], v[22:23], 0, v[20:21]
	global_load_dwordx2 v[28:29], v[20:21], off
	global_load_dwordx2 v[32:33], v[20:21], off offset:512
	global_load_dwordx2 v[38:39], v[20:21], off offset:1024
	global_load_dwordx2 v[40:41], v[20:21], off offset:1536
	v_cmp_lt_i32_e32 vcc, s21, v18
	s_waitcnt vmcnt(3)
	v_lshlrev_b32_e32 v30, 16, v28
	v_and_b32_e32 v31, 0xffff0000, v28
	v_lshlrev_b32_e32 v34, 16, v29
	v_and_b32_e32 v35, 0xffff0000, v29
	s_waitcnt vmcnt(2)
	v_lshlrev_b32_e32 v28, 16, v32
	v_and_b32_e32 v29, 0xffff0000, v32
	v_lshlrev_b32_e32 v32, 16, v33
	v_and_b32_e32 v33, 0xffff0000, v33
	s_waitcnt vmcnt(1)
	v_lshlrev_b32_e32 v36, 16, v38
	v_and_b32_e32 v37, 0xffff0000, v38
	v_lshlrev_b32_e32 v38, 16, v39
	v_and_b32_e32 v39, 0xffff0000, v39
	s_waitcnt vmcnt(0)
	v_lshlrev_b32_e32 v20, 16, v40
	v_and_b32_e32 v21, 0xffff0000, v40
	v_lshlrev_b32_e32 v40, 16, v41
	v_and_b32_e32 v41, 0xffff0000, v41
	s_and_saveexec_b64 s[48:49], vcc
	s_cbranch_execz .LBB0_16
	v_add_u32_e32 v0, 0xffff8000, v18
	v_lshlrev_b64 v[18:19], 12, v[0:1]
	v_lshl_add_u64 v[18:19], v[24:25], 0, v[18:19]
	s_mov_b32 s101, 0
	global_load_dwordx4 v[64:67], v[18:19], off
	global_load_dwordx4 v[68:71], v[18:19], off offset:1024
	global_load_dwordx4 v[72:75], v[18:19], off offset:2048
	global_load_dwordx4 v[76:79], v[18:19], off offset:3072
	s_mov_b32 s100, 0x100000
	v_lshl_add_u64 v[56:57], v[18:19], 0, s[100:101]
	global_load_dwordx4 v[80:83], v[56:57], off
	global_load_dwordx4 v[84:87], v[56:57], off offset:1024
	global_load_dwordx4 v[88:91], v[56:57], off offset:2048
	global_load_dwordx4 v[92:95], v[56:57], off offset:3072
	s_mov_b32 s100, 0x200000
	v_lshl_add_u64 v[56:57], v[18:19], 0, s[100:101]
	global_load_dwordx4 v[96:99], v[56:57], off
	global_load_dwordx4 v[100:103], v[56:57], off offset:1024
	global_load_dwordx4 v[104:107], v[56:57], off offset:2048
	global_load_dwordx4 v[108:111], v[56:57], off offset:3072
	s_mov_b32 s100, 0x300000
	v_lshl_add_u64 v[56:57], v[18:19], 0, s[100:101]
	global_load_dwordx4 v[112:115], v[56:57], off
	global_load_dwordx4 v[116:119], v[56:57], off offset:1024
	global_load_dwordx4 v[120:123], v[56:57], off offset:2048
	global_load_dwordx4 v[124:127], v[56:57], off offset:3072
	s_mov_b32 s100, 0x400000
	v_lshl_add_u64 v[56:57], v[18:19], 0, s[100:101]
	global_load_dwordx4 v[128:131], v[56:57], off
	global_load_dwordx4 v[132:135], v[56:57], off offset:1024
	global_load_dwordx4 v[136:139], v[56:57], off offset:2048
	global_load_dwordx4 v[140:143], v[56:57], off offset:3072
	s_mov_b32 s100, 0x500000
	v_lshl_add_u64 v[56:57], v[18:19], 0, s[100:101]
	global_load_dwordx4 v[144:147], v[56:57], off
	global_load_dwordx4 v[148:151], v[56:57], off offset:1024
	global_load_dwordx4 v[152:155], v[56:57], off offset:2048
	global_load_dwordx4 v[156:159], v[56:57], off offset:3072
	s_waitcnt vmcnt(23)
	v_pk_add_f32 v[30:31], v[30:31], v[64:65]
	v_pk_add_f32 v[34:35], v[34:35], v[66:67]
	s_waitcnt vmcnt(22)
	v_pk_add_f32 v[28:29], v[28:29], v[68:69]
	v_pk_add_f32 v[32:33], v[32:33], v[70:71]
	s_waitcnt vmcnt(21)
	v_pk_add_f32 v[36:37], v[36:37], v[72:73]
	v_pk_add_f32 v[38:39], v[38:39], v[74:75]
	s_waitcnt vmcnt(20)
	v_pk_add_f32 v[20:21], v[20:21], v[76:77]
	v_pk_add_f32 v[40:41], v[40:41], v[78:79]
	s_waitcnt vmcnt(19)
	v_pk_add_f32 v[30:31], v[30:31], v[80:81]
	v_pk_add_f32 v[34:35], v[34:35], v[82:83]
	s_waitcnt vmcnt(18)
	v_pk_add_f32 v[28:29], v[28:29], v[84:85]
	v_pk_add_f32 v[32:33], v[32:33], v[86:87]
	s_waitcnt vmcnt(17)
	v_pk_add_f32 v[36:37], v[36:37], v[88:89]
	v_pk_add_f32 v[38:39], v[38:39], v[90:91]
	s_waitcnt vmcnt(16)
	v_pk_add_f32 v[20:21], v[20:21], v[92:93]
	v_pk_add_f32 v[40:41], v[40:41], v[94:95]
	s_waitcnt vmcnt(15)
	v_pk_add_f32 v[30:31], v[30:31], v[96:97]
	v_pk_add_f32 v[34:35], v[34:35], v[98:99]
	s_waitcnt vmcnt(14)
	v_pk_add_f32 v[28:29], v[28:29], v[100:101]
	v_pk_add_f32 v[32:33], v[32:33], v[102:103]
	s_waitcnt vmcnt(13)
	v_pk_add_f32 v[36:37], v[36:37], v[104:105]
	v_pk_add_f32 v[38:39], v[38:39], v[106:107]
	s_waitcnt vmcnt(12)
	v_pk_add_f32 v[20:21], v[20:21], v[108:109]
	v_pk_add_f32 v[40:41], v[40:41], v[110:111]
	s_waitcnt vmcnt(11)
	v_pk_add_f32 v[30:31], v[30:31], v[112:113]
	v_pk_add_f32 v[34:35], v[34:35], v[114:115]
	s_waitcnt vmcnt(10)
	v_pk_add_f32 v[28:29], v[28:29], v[116:117]
	v_pk_add_f32 v[32:33], v[32:33], v[118:119]
	s_waitcnt vmcnt(9)
	v_pk_add_f32 v[36:37], v[36:37], v[120:121]
	v_pk_add_f32 v[38:39], v[38:39], v[122:123]
	s_waitcnt vmcnt(8)
; __device__ void final_norm(const Params& p, const bf16_t* hb, const float* gain, float* out) {
;     ...
;         if (row >= MP - 256) { const float* pt = (const float*)(p.ws + WS_PART) + (size_t)(row - (MP - 256)) * DM + lane * 4;
;             for (int sl = 0; sl < 11; ++sl)
; #pragma unroll
;                 for (int i = 0; i < 4; ++i) v[i] += *(const f32x4*)(pt + (size_t)sl * 256 * DM + 256 * i); }
	v_pk_add_f32 v[20:21], v[20:21], v[124:125]
	v_pk_add_f32 v[40:41], v[40:41], v[126:127]
	s_waitcnt vmcnt(7)
	v_pk_add_f32 v[30:31], v[30:31], v[128:129]
	v_pk_add_f32 v[34:35], v[34:35], v[130:131]
	s_waitcnt vmcnt(6)
	v_pk_add_f32 v[28:29], v[28:29], v[132:133]
	v_pk_add_f32 v[32:33], v[32:33], v[134:135]
	s_waitcnt vmcnt(5)
	v_pk_add_f32 v[36:37], v[36:37], v[136:137]
	v_pk_add_f32 v[38:39], v[38:39], v[138:139]
	s_waitcnt vmcnt(4)
	v_pk_add_f32 v[20:21], v[20:21], v[140:141]
	v_pk_add_f32 v[40:41], v[40:41], v[142:143]
	s_waitcnt vmcnt(3)
	v_pk_add_f32 v[30:31], v[30:31], v[144:145]
	v_pk_add_f32 v[34:35], v[34:35], v[146:147]
	s_waitcnt vmcnt(2)
	v_pk_add_f32 v[28:29], v[28:29], v[148:149]
	v_pk_add_f32 v[32:33], v[32:33], v[150:151]
	s_waitcnt vmcnt(1)
	v_pk_add_f32 v[36:37], v[36:37], v[152:153]
	v_pk_add_f32 v[38:39], v[38:39], v[154:155]
	s_waitcnt vmcnt(0)
	v_pk_add_f32 v[20:21], v[20:21], v[156:157]
	v_pk_add_f32 v[40:41], v[40:41], v[158:159]
	s_mov_b32 s100, 0x600000
	v_lshl_add_u64 v[56:57], v[18:19], 0, s[100:101]
	global_load_dwordx4 v[64:67], v[56:57], off
	global_load_dwordx4 v[68:71], v[56:57], off offset:1024
	global_load_dwordx4 v[72:75], v[56:57], off offset:2048
	global_load_dwordx4 v[76:79], v[56:57], off offset:3072
	s_mov_b32 s100, 0x700000
	v_lshl_add_u64 v[56:57], v[18:19], 0, s[100:101]
	global_load_dwordx4 v[80:83], v[56:57], off
	global_load_dwordx4 v[84:87], v[56:57], off offset:1024
	global_load_dwordx4 v[88:91], v[56:57], off offset:2048
	global_load_dwordx4 v[92:95], v[56:57], off offset:3072
	s_mov_b32 s100, 0x800000
	v_lshl_add_u64 v[56:57], v[18:19], 0, s[100:101]
	global_load_dwordx4 v[96:99], v[56:57], off
	global_load_dwordx4 v[100:103], v[56:57], off offset:1024
	global_load_dwordx4 v[104:107], v[56:57], off offset:2048
	global_load_dwordx4 v[108:111], v[56:57], off offset:3072
	s_mov_b32 s100, 0x900000
	v_lshl_add_u64 v[56:57], v[18:19], 0, s[100:101]
	global_load_dwordx4 v[112:115], v[56:57], off
	global_load_dwordx4 v[116:119], v[56:57], off offset:1024
	global_load_dwordx4 v[120:123], v[56:57], off offset:2048
	global_load_dwordx4 v[124:127], v[56:57], off offset:3072
	s_mov_b32 s100, 0xa00000
	v_lshl_add_u64 v[56:57], v[18:19], 0, s[100:101]
	global_load_dwordx4 v[128:131], v[56:57], off
	global_load_dwordx4 v[132:135], v[56:57], off offset:1024
	global_load_dwordx4 v[136:139], v[56:57], off offset:2048
	global_load_dwordx4 v[140:143], v[56:57], off offset:3072
	s_waitcnt vmcnt(19)
	v_pk_add_f32 v[30:31], v[30:31], v[64:65]
	v_pk_add_f32 v[34:35], v[34:35], v[66:67]
	s_waitcnt vmcnt(18)
	v_pk_add_f32 v[28:29], v[28:29], v[68:69]
	v_pk_add_f32 v[32:33], v[32:33], v[70:71]
	s_waitcnt vmcnt(17)
	v_pk_add_f32 v[36:37], v[36:37], v[72:73]
	v_pk_add_f32 v[38:39], v[38:39], v[74:75]
	s_waitcnt vmcnt(16)
	v_pk_add_f32 v[20:21], v[20:21], v[76:77]
	v_pk_add_f32 v[40:41], v[40:41], v[78:79]
	s_waitcnt vmcnt(15)
	v_pk_add_f32 v[30:31], v[30:31], v[80:81]
	v_pk_add_f32 v[34:35], v[34:35], v[82:83]
	s_waitcnt vmcnt(14)
	v_pk_add_f32 v[28:29], v[28:29], v[84:85]
	v_pk_add_f32 v[32:33], v[32:33], v[86:87]
	s_waitcnt vmcnt(13)
	v_pk_add_f32 v[36:37], v[36:37], v[88:89]
	v_pk_add_f32 v[38:39], v[38:39], v[90:91]
	s_waitcnt vmcnt(12)
	v_pk_add_f32 v[20:21], v[20:21], v[92:93]
	v_pk_add_f32 v[40:41], v[40:41], v[94:95]
	s_waitcnt vmcnt(11)
	v_pk_add_f32 v[30:31], v[30:31], v[96:97]
	v_pk_add_f32 v[34:35], v[34:35], v[98:99]
	s_waitcnt vmcnt(10)
	v_pk_add_f32 v[28:29], v[28:29], v[100:101]
	v_pk_add_f32 v[32:33], v[32:33], v[102:103]
	s_waitcnt vmcnt(9)
	v_pk_add_f32 v[36:37], v[36:37], v[104:105]
	v_pk_add_f32 v[38:39], v[38:39], v[106:107]
	s_waitcnt vmcnt(8)
	v_pk_add_f32 v[20:21], v[20:21], v[108:109]
	v_pk_add_f32 v[40:41], v[40:41], v[110:111]
	s_waitcnt vmcnt(7)
	v_pk_add_f32 v[30:31], v[30:31], v[112:113]
	v_pk_add_f32 v[34:35], v[34:35], v[114:115]
	s_waitcnt vmcnt(6)
	v_pk_add_f32 v[28:29], v[28:29], v[116:117]
	v_pk_add_f32 v[32:33], v[32:33], v[118:119]
	s_waitcnt vmcnt(5)
	v_pk_add_f32 v[36:37], v[36:37], v[120:121]
	v_pk_add_f32 v[38:39], v[38:39], v[122:123]
	s_waitcnt vmcnt(4)
	v_pk_add_f32 v[20:21], v[20:21], v[124:125]
	v_pk_add_f32 v[40:41], v[40:41], v[126:127]
	s_waitcnt vmcnt(3)
	v_pk_add_f32 v[30:31], v[30:31], v[128:129]
	v_pk_add_f32 v[34:35], v[34:35], v[130:131]
	s_waitcnt vmcnt(2)
	v_pk_add_f32 v[28:29], v[28:29], v[132:133]
	v_pk_add_f32 v[32:33], v[32:33], v[134:135]
	s_waitcnt vmcnt(1)
	v_pk_add_f32 v[36:37], v[36:37], v[136:137]
	v_pk_add_f32 v[38:39], v[38:39], v[138:139]
	s_waitcnt vmcnt(0)
	v_pk_add_f32 v[20:21], v[20:21], v[140:141]
	v_pk_add_f32 v[40:41], v[40:41], v[142:143]
	s_branch .LBB0_16
